# v20 plus removal of compiler asm-block pad s_nops in the GEMM K-loops (LDS->MFMA needs only the waitcnt)
# speedup vs baseline: 1.0053x; 1.0053x over previous
.LBB0_57:
	s_cmp_gt_i32 s68, 0
	s_waitcnt vmcnt(6)
	s_cselect_b32 s69, -1, 2
	s_mul_i32 s70, s68, 0x6000
	s_waitcnt lgkmcnt(0)
	s_add_i32 s69, s69, s68
	v_add_u32_e32 v135, s70, v149
	v_add_u32_e32 v0, s70, v148
	s_mulk_i32 s69, 0x6000
	v_add_u32_e32 v164, v135, v152
	s_barrier
	v_lshl_add_u64 v[180:181], v[138:139], 0, s[0:1]
	v_add_u32_e32 v159, s69, v146
	v_lshl_add_u64 v[184:185], v[136:137], 0, s[0:1]
	v_add_u32_e32 v192, s69, v147
	v_add_u32_e32 v176, v0, v152
	ds_read_b128 v[140:143], v176
	ds_read_b128 v[160:163], v164
	ds_read_b128 v[164:167], v164 offset:2048
	v_lshl_add_u64 v[182:183], v[180:181], 0, s[88:89]
	v_lshl_add_u64 v[186:187], v[184:185], 0, s[88:89]
	v_add_u32_e32 v193, 0x4000, v192
	v_lshl_add_u64 v[188:189], v[180:181], 0, s[90:91]
	v_add_u32_e32 v194, 0x400, v159
	v_lshl_add_u64 v[190:191], v[180:181], 0, s[78:79]
	v_add_u32_e32 v195, 0x800, v159
	ds_read_b128 v[168:171], v176 offset:2048
	ds_read_b128 v[172:175], v176 offset:4096
	ds_read_b128 v[176:179], v176 offset:6144
	s_waitcnt lgkmcnt(3)
	s_setprio 1
	v_mfma_f32_32x32x16_bf16 v[114:129], v[140:143], v[160:163], v[114:129]
	v_mfma_f32_32x32x16_bf16 v[98:113], v[140:143], v[164:167], v[98:113]
	v_readfirstlane_b32 s69, v159
	s_mov_b32 m0, s69
	s_nop 0
	global_load_lds_dwordx4 v[182:183], off
	s_waitcnt lgkmcnt(2)
	v_mfma_f32_32x32x16_bf16 v[82:97], v[168:171], v[160:163], v[82:97]
	v_mfma_f32_32x32x16_bf16 v[66:81], v[168:171], v[164:167], v[66:81]
	v_readfirstlane_b32 s69, v194
	s_mov_b32 m0, s69
	s_nop 0
	global_load_lds_dwordx4 v[188:189], off
	s_waitcnt lgkmcnt(1)
	v_mfma_f32_32x32x16_bf16 v[50:65], v[172:175], v[160:163], v[50:65]
	v_mfma_f32_32x32x16_bf16 v[34:49], v[172:175], v[164:167], v[34:49]
	v_readfirstlane_b32 s69, v195
	s_mov_b32 m0, s69
	s_nop 0
	global_load_lds_dwordx4 v[190:191], off
	s_waitcnt lgkmcnt(0)
	v_mfma_f32_32x32x16_bf16 v[18:33], v[176:179], v[160:163], v[18:33]
	v_mfma_f32_32x32x16_bf16 v[2:17], v[176:179], v[164:167], v[2:17]
	s_setprio 0
	v_add_u32_e32 v0, v0, v153
	v_add_u32_e32 v135, v135, v153
	ds_read_b128 v[140:143], v0
	ds_read_b128 v[160:163], v135
	ds_read_b128 v[164:167], v135 offset:2048
	ds_read_b128 v[168:171], v0 offset:2048
	ds_read_b128 v[172:175], v0 offset:4096
	ds_read_b128 v[176:179], v0 offset:6144
	s_waitcnt lgkmcnt(3)
	s_setprio 1
	v_mfma_f32_32x32x16_bf16 v[114:129], v[140:143], v[160:163], v[114:129]
	v_mfma_f32_32x32x16_bf16 v[98:113], v[140:143], v[164:167], v[98:113]
	v_add_u32_e32 v0, 0xc00, v159
	v_lshl_add_u64 v[140:141], v[180:181], 0, s[76:77]
	v_readfirstlane_b32 s69, v0
	s_mov_b32 m0, s69
	s_nop 0
	global_load_lds_dwordx4 v[140:141], off
	s_waitcnt lgkmcnt(2)
	v_mfma_f32_32x32x16_bf16 v[82:97], v[168:171], v[160:163], v[82:97]
	v_mfma_f32_32x32x16_bf16 v[66:81], v[168:171], v[164:167], v[66:81]
	v_readfirstlane_b32 s69, v193
	s_mov_b32 m0, s69
	s_nop 0
	global_load_lds_dwordx4 v[186:187], off
	s_waitcnt lgkmcnt(1)
	v_mfma_f32_32x32x16_bf16 v[50:65], v[172:175], v[160:163], v[50:65]
	v_mfma_f32_32x32x16_bf16 v[34:49], v[172:175], v[164:167], v[34:49]
	v_add_u32_e32 v0, 0x4400, v192
	v_lshl_add_u64 v[140:141], v[184:185], 0, s[90:91]
	v_readfirstlane_b32 s69, v0
	s_mov_b32 m0, s69
	s_nop 0
	global_load_lds_dwordx4 v[140:141], off
	s_waitcnt lgkmcnt(0)
	v_mfma_f32_32x32x16_bf16 v[18:33], v[176:179], v[160:163], v[18:33]
	v_mfma_f32_32x32x16_bf16 v[2:17], v[176:179], v[164:167], v[2:17]
	s_setprio 0
	s_add_i32 s69, s68, 1
	s_cmp_lt_i32 s68, 2
	s_cselect_b32 s68, s69, 0
	s_add_u32 s0, s0, 0x80
	s_addc_u32 s1, s1, 0
	s_cmpk_eq_i32 s0, 0xf00
	s_cbranch_scc0 .LBB0_57
	s_waitcnt vmcnt(6)
	s_mul_i32 s0, s68, 0x6000
	s_waitcnt lgkmcnt(0)
	v_add_u32_e32 v135, s0, v149
	v_add_u32_e32 v0, s0, v148
	v_add_u32_e32 v160, v135, v152
	s_barrier
	v_add_u32_e32 v159, v0, v152
	ds_read_b128 v[136:139], v159
	ds_read_b128 v[140:143], v160
	ds_read_b128 v[160:163], v160 offset:2048
	ds_read_b128 v[164:167], v159 offset:2048
	ds_read_b128 v[168:171], v159 offset:4096
	ds_read_b128 v[172:175], v159 offset:6144
	s_waitcnt lgkmcnt(3)
	s_setprio 1
	v_mfma_f32_32x32x16_bf16 v[114:129], v[136:139], v[140:143], v[114:129]
	v_mfma_f32_32x32x16_bf16 v[98:113], v[136:139], v[160:163], v[98:113]
	s_waitcnt lgkmcnt(2)
	v_mfma_f32_32x32x16_bf16 v[82:97], v[164:167], v[140:143], v[82:97]
	v_mfma_f32_32x32x16_bf16 v[66:81], v[164:167], v[160:163], v[66:81]
	s_waitcnt lgkmcnt(1)
	v_mfma_f32_32x32x16_bf16 v[50:65], v[168:171], v[140:143], v[50:65]
	v_mfma_f32_32x32x16_bf16 v[34:49], v[168:171], v[160:163], v[34:49]
	s_waitcnt lgkmcnt(0)
	v_mfma_f32_32x32x16_bf16 v[18:33], v[172:175], v[140:143], v[18:33]
	v_mfma_f32_32x32x16_bf16 v[2:17], v[172:175], v[160:163], v[2:17]
	s_setprio 0
	v_add_u32_e32 v0, v0, v153
	v_add_u32_e32 v135, v135, v153
	ds_read_b128 v[136:139], v0
	ds_read_b128 v[140:143], v135
	ds_read_b128 v[160:163], v135 offset:2048
	ds_read_b128 v[164:167], v0 offset:2048
	ds_read_b128 v[168:171], v0 offset:4096
	ds_read_b128 v[172:175], v0 offset:6144
	s_waitcnt lgkmcnt(3)
	s_setprio 1
	v_mfma_f32_32x32x16_bf16 v[114:129], v[136:139], v[140:143], v[114:129]
	v_mfma_f32_32x32x16_bf16 v[98:113], v[136:139], v[160:163], v[98:113]
	s_waitcnt lgkmcnt(2)
	v_mfma_f32_32x32x16_bf16 v[82:97], v[164:167], v[140:143], v[82:97]
	v_mfma_f32_32x32x16_bf16 v[66:81], v[164:167], v[160:163], v[66:81]
	s_waitcnt lgkmcnt(1)
	v_mfma_f32_32x32x16_bf16 v[50:65], v[168:171], v[140:143], v[50:65]
	v_mfma_f32_32x32x16_bf16 v[34:49], v[168:171], v[160:163], v[34:49]
	s_waitcnt lgkmcnt(0)
	v_mfma_f32_32x32x16_bf16 v[18:33], v[172:175], v[140:143], v[18:33]
	v_mfma_f32_32x32x16_bf16 v[2:17], v[172:175], v[160:163], v[2:17]
	s_setprio 0
	s_waitcnt vmcnt(0)
	s_waitcnt lgkmcnt(0)
	s_barrier
	ds_read_b128 v[136:139], v154
	ds_read_b128 v[140:143], v155
	ds_read_b128 v[160:163], v155 offset:2048
	ds_read_b128 v[164:167], v154 offset:2048
	ds_read_b128 v[168:171], v154 offset:4096
	ds_read_b128 v[172:175], v154 offset:6144
	s_waitcnt lgkmcnt(3)
	s_setprio 1
	v_mfma_f32_32x32x16_bf16 v[114:129], v[136:139], v[140:143], v[114:129]
	v_mfma_f32_32x32x16_bf16 v[98:113], v[136:139], v[160:163], v[98:113]
	s_waitcnt lgkmcnt(2)
	v_mfma_f32_32x32x16_bf16 v[82:97], v[164:167], v[140:143], v[82:97]
	v_mfma_f32_32x32x16_bf16 v[66:81], v[164:167], v[160:163], v[66:81]
	s_waitcnt lgkmcnt(1)
	v_mfma_f32_32x32x16_bf16 v[50:65], v[168:171], v[140:143], v[50:65]
	v_mfma_f32_32x32x16_bf16 v[34:49], v[168:171], v[160:163], v[34:49]
	s_waitcnt lgkmcnt(0)
	v_mfma_f32_32x32x16_bf16 v[18:33], v[172:175], v[140:143], v[18:33]
	v_mfma_f32_32x32x16_bf16 v[2:17], v[172:175], v[160:163], v[2:17]
	s_setprio 0
	ds_read_b128 v[136:139], v156
	ds_read_b128 v[140:143], v157
	ds_read_b128 v[160:163], v157 offset:2048
	ds_read_b128 v[164:167], v156 offset:2048
	ds_read_b128 v[168:171], v156 offset:4096
	ds_read_b128 v[172:175], v156 offset:6144
	s_waitcnt lgkmcnt(3)
	s_setprio 1
	v_mfma_f32_32x32x16_bf16 v[114:129], v[136:139], v[140:143], v[114:129]
	v_mfma_f32_32x32x16_bf16 v[98:113], v[136:139], v[160:163], v[98:113]
	s_waitcnt lgkmcnt(2)
	v_mfma_f32_32x32x16_bf16 v[82:97], v[164:167], v[140:143], v[82:97]
	v_mfma_f32_32x32x16_bf16 v[66:81], v[164:167], v[160:163], v[66:81]
	s_waitcnt lgkmcnt(1)
	v_mfma_f32_32x32x16_bf16 v[50:65], v[168:171], v[140:143], v[50:65]
	v_mfma_f32_32x32x16_bf16 v[34:49], v[168:171], v[160:163], v[34:49]
	s_waitcnt lgkmcnt(0)
	v_mfma_f32_32x32x16_bf16 v[18:33], v[172:175], v[140:143], v[18:33]
	v_mfma_f32_32x32x16_bf16 v[2:17], v[172:175], v[160:163], v[2:17]
	s_setprio 0
	v_add_u32_e32 v138, s29, v151
	v_or_b32_e32 v136, s31, v150
	v_ashrrev_i32_e32 v139, 31, v138
	v_lshlrev_b64 v[142:143], 10, v[138:139]
	v_ashrrev_i32_e32 v137, 31, v136
	v_lshl_add_u64 v[142:143], v[142:143], 0, v[136:137]
	s_ashr_i32 s0, s28, 4
	v_lshlrev_b64 v[160:161], 2, v[142:143]
	s_add_i32 s0, s0, s10
	v_lshl_add_u64 v[142:143], s[98:99], 0, v[160:161]
	s_movk_i32 s29, 0x2000
	s_mul_hi_i32 s1, s0, 0x3000
	s_mulk_i32 s0, 0x3000
	v_add_co_u32_e32 v162, vcc, s29, v142
	s_add_u32 s0, s4, s0
	s_nop 0
	v_addc_co_u32_e32 v163, vcc, 0, v143, vcc
	s_addc_u32 s1, s5, s1
	v_add_co_u32_e32 v164, vcc, s73, v142
	s_add_u32 s0, s0, 0x2000
	s_nop 0
	v_addc_co_u32_e32 v165, vcc, 0, v143, vcc
	s_addc_u32 s1, s1, 0
	v_add_co_u32_e32 v166, vcc, s75, v142
	v_lshl_add_u64 v[140:141], v[136:137], 2, s[0:1]
	s_nop 0
	v_addc_co_u32_e32 v167, vcc, 0, v143, vcc
	s_waitcnt vmcnt(0) lgkmcnt(0)
	s_barrier
	global_load_dword v0, v[140:141], off
	v_add_co_u32_e32 v168, vcc, s95, v142
	s_mov_b32 s31, 0x11000
	s_nop 0
	v_addc_co_u32_e32 v169, vcc, 0, v143, vcc
	global_load_dword v135, v[142:143], off nt
	global_load_dword v139, v[162:163], off offset:-4096 nt
	global_load_dword v159, v[162:163], off nt
	global_load_dword v188, v[166:167], off offset:-4096 nt
	global_load_dword v189, v[166:167], off nt
	global_load_dword v190, v[168:169], off offset:-4096 nt
	global_load_dword v191, v[168:169], off nt
	global_load_dword v186, v[164:165], off nt
	v_add_co_u32_e32 v170, vcc, s31, v142
	s_mov_b32 s36, 0x13000
	s_nop 0
	v_addc_co_u32_e32 v171, vcc, 0, v143, vcc
	v_add_co_u32_e32 v172, vcc, s36, v142
	s_mov_b32 s37, 0x19000
	s_nop 0
	v_addc_co_u32_e32 v173, vcc, 0, v143, vcc
	global_load_dword v192, v[170:171], off offset:-4096 nt
	global_load_dword v193, v[170:171], off nt
	v_add_co_u32_e32 v174, vcc, s37, v142
	s_mov_b32 s39, 0x1b000
	s_nop 0
	v_addc_co_u32_e32 v175, vcc, 0, v143, vcc
	global_load_dword v194, v[172:173], off offset:-4096 nt
	global_load_dword v195, v[172:173], off nt
	v_add_co_u32_e32 v176, vcc, s39, v142
	global_load_dword v196, v[174:175], off offset:-4096 nt
	global_load_dword v197, v[174:175], off nt
	v_addc_co_u32_e32 v177, vcc, 0, v143, vcc
	global_load_dword v198, v[176:177], off offset:-4096 nt
	global_load_dword v199, v[176:177], off nt
	s_movk_i32 s28, 0x1000
	v_add_co_u32_e32 v178, vcc, s28, v142
	v_lshl_add_u64 v[160:161], s[56:57], 0, v[160:161]
	s_nop 0
	v_addc_co_u32_e32 v179, vcc, 0, v143, vcc
	v_add_co_u32_e32 v180, vcc, s94, v142
	s_mov_b32 s38, 0x1a000
	s_nop 0
	v_addc_co_u32_e32 v181, vcc, 0, v143, vcc
	v_add_co_u32_e32 v182, vcc, s87, v142
	s_add_i32 s34, s34, s30
	s_nop 0
	v_addc_co_u32_e32 v183, vcc, 0, v143, vcc
	v_add_co_u32_e32 v184, vcc, s29, v160
	s_cmp_ge_i32 s34, s35
	s_nop 0
	v_addc_co_u32_e32 v185, vcc, 0, v161, vcc
	s_waitcnt vmcnt(15)
	v_fmac_f32_e32 v135, v114, v0
	s_waitcnt vmcnt(13)
	v_fmac_f32_e32 v159, v116, v0
	v_add_co_u32_e32 v116, vcc, s73, v160
	v_fmac_f32_e32 v139, v115, v0
	global_store_dword v[160:161], v135, off nt
	global_store_dword v[184:185], v139, off offset:-4096 nt
	s_waitcnt vmcnt(10)
	v_fmac_f32_e32 v186, v117, v0
	v_addc_co_u32_e32 v117, vcc, 0, v161, vcc
	global_store_dword v[116:117], v186, off nt
	v_add_co_u32_e32 v186, vcc, s75, v160
	v_fmac_f32_e32 v188, v118, v0
	s_nop 0
	v_addc_co_u32_e32 v187, vcc, 0, v161, vcc
	v_add_co_u32_e32 v118, vcc, s95, v160
	v_fmac_f32_e32 v189, v119, v0
	s_nop 0
	v_addc_co_u32_e32 v119, vcc, 0, v161, vcc
	v_fmac_f32_e32 v190, v120, v0
	v_add_co_u32_e32 v120, vcc, s31, v160
	v_fmac_f32_e32 v191, v121, v0
	s_nop 0
	v_addc_co_u32_e32 v121, vcc, 0, v161, vcc
	s_waitcnt vmcnt(10)
	v_fmac_f32_e32 v192, v122, v0
	v_add_co_u32_e32 v122, vcc, s36, v160
	s_waitcnt vmcnt(9)
	v_fmac_f32_e32 v193, v123, v0
	v_addc_co_u32_e32 v123, vcc, 0, v161, vcc
	s_waitcnt vmcnt(8)
	v_fmac_f32_e32 v194, v124, v0
	v_add_co_u32_e32 v124, vcc, s37, v160
	s_waitcnt vmcnt(7)
	v_fmac_f32_e32 v195, v125, v0
	v_addc_co_u32_e32 v125, vcc, 0, v161, vcc
	v_or_b32_e32 v114, 32, v136
	s_waitcnt vmcnt(6)
	v_fmac_f32_e32 v196, v126, v0
	v_add_co_u32_e32 v126, vcc, s39, v160
	v_ashrrev_i32_e32 v115, 31, v114
	s_waitcnt vmcnt(5)
	v_fmac_f32_e32 v197, v127, v0
	s_waitcnt vmcnt(4)
	v_fmac_f32_e32 v198, v128, v0
	v_addc_co_u32_e32 v127, vcc, 0, v161, vcc
	s_waitcnt vmcnt(3)
	v_fmac_f32_e32 v199, v129, v0
	v_lshl_add_u64 v[114:115], v[114:115], 2, s[0:1]
	s_mov_b32 s0, 0x10000
	global_store_dword v[184:185], v159, off nt
	global_store_dword v[186:187], v188, off offset:-4096 nt
	global_store_dword v[186:187], v189, off nt
	global_store_dword v[118:119], v190, off offset:-4096 nt
	global_store_dword v[118:119], v191, off nt
	global_store_dword v[120:121], v192, off offset:-4096 nt
	global_store_dword v[120:121], v193, off nt
	global_store_dword v[122:123], v194, off offset:-4096 nt
	global_store_dword v[122:123], v195, off nt
	global_store_dword v[124:125], v196, off offset:-4096 nt
	global_store_dword v[124:125], v197, off nt
	global_store_dword v[126:127], v198, off offset:-4096 nt
	global_store_dword v[126:127], v199, off nt
	v_add_co_u32_e32 v128, vcc, s0, v142
	global_load_dword v0, v[114:115], off
	global_load_dword v135, v[142:143], off offset:128 nt
	global_load_dword v139, v[178:179], off offset:128 nt
	v_addc_co_u32_e32 v129, vcc, 0, v143, vcc
	global_load_dword v159, v[162:163], off offset:128 nt
	global_load_dword v178, v[164:165], off offset:128 nt
	global_load_dword v179, v[180:181], off offset:128 nt
	s_nop 0
	global_load_dword v180, v[166:167], off offset:128 nt
	v_add_co_u32_e32 v162, vcc, s72, v142
	s_mov_b32 s1, 0x18000
	s_nop 0
	v_addc_co_u32_e32 v163, vcc, 0, v143, vcc
	global_load_dword v181, v[182:183], off offset:128 nt
	s_nop 0
	global_load_dword v182, v[128:129], off offset:128 nt
	global_load_dword v183, v[168:169], off offset:128 nt
	global_load_dword v188, v[170:171], off offset:128 nt
	v_add_co_u32_e32 v128, vcc, s1, v142
	s_waitcnt vmcnt(9)
	v_fmac_f32_e32 v135, v98, v0
	v_addc_co_u32_e32 v129, vcc, 0, v143, vcc
	global_load_dword v189, v[162:163], off offset:128 nt
	global_load_dword v190, v[128:129], off offset:128 nt
	s_nop 0
	global_load_dword v172, v[172:173], off offset:128 nt
	s_nop 0
	global_load_dword v173, v[174:175], off offset:128 nt
	v_add_co_u32_e32 v128, vcc, s38, v142
	v_or_b32_e32 v98, 32, v138
	s_nop 0
	v_addc_co_u32_e32 v129, vcc, 0, v143, vcc
	global_load_dword v174, v[128:129], off offset:128 nt
	global_load_dword v175, v[176:177], off offset:128 nt
	v_add_co_u32_e32 v128, vcc, s28, v160
	s_waitcnt vmcnt(14)
	v_fmac_f32_e32 v139, v99, v0
	v_addc_co_u32_e32 v129, vcc, 0, v161, vcc
	v_add_co_u32_e32 v142, vcc, s94, v160
	v_ashrrev_i32_e32 v99, 31, v98
	s_nop 0
	v_addc_co_u32_e32 v143, vcc, 0, v161, vcc
	v_add_co_u32_e32 v162, vcc, s87, v160
	v_lshlrev_b64 v[98:99], 10, v[98:99]
	s_nop 0
	v_addc_co_u32_e32 v163, vcc, 0, v161, vcc
	v_add_co_u32_e32 v164, vcc, s0, v160
	v_lshl_add_u64 v[98:99], v[98:99], 0, v[136:137]
	s_nop 0
	v_addc_co_u32_e32 v165, vcc, 0, v161, vcc
	v_add_co_u32_e32 v166, vcc, s72, v160
	v_lshlrev_b64 v[98:99], 2, v[98:99]
	s_nop 0
	v_addc_co_u32_e32 v167, vcc, 0, v161, vcc
	v_add_co_u32_e32 v168, vcc, s1, v160
	s_waitcnt vmcnt(13)
	v_fmac_f32_e32 v159, v100, v0
	v_addc_co_u32_e32 v169, vcc, 0, v161, vcc
	v_add_co_u32_e32 v170, vcc, s38, v160
	s_waitcnt vmcnt(12)
	v_fmac_f32_e32 v178, v101, v0
	v_addc_co_u32_e32 v171, vcc, 0, v161, vcc
	v_lshl_add_u64 v[100:101], s[98:99], 0, v[98:99]
	s_waitcnt vmcnt(11)
	v_fmac_f32_e32 v179, v102, v0
	v_add_co_u32_e32 v102, vcc, s29, v100
	s_waitcnt vmcnt(10)
	v_fmac_f32_e32 v180, v103, v0
	v_addc_co_u32_e32 v103, vcc, 0, v101, vcc
	s_waitcnt vmcnt(9)
	v_fmac_f32_e32 v181, v104, v0
	s_waitcnt vmcnt(7)
	v_fmac_f32_e32 v183, v105, v0
	v_fmac_f32_e32 v182, v106, v0
	s_waitcnt vmcnt(6)
	v_fmac_f32_e32 v188, v107, v0
	v_add_co_u32_e32 v104, vcc, s73, v100
	global_store_dword v[160:161], v135, off offset:128 nt
	global_store_dword v[128:129], v139, off offset:128 nt
	global_store_dword v[184:185], v159, off offset:128 nt
	global_store_dword v[116:117], v178, off offset:128 nt
	global_store_dword v[142:143], v179, off offset:128 nt
	global_store_dword v[186:187], v180, off offset:128 nt
	global_store_dword v[162:163], v181, off offset:128 nt
	global_store_dword v[118:119], v183, off offset:128 nt
	global_store_dword v[164:165], v182, off offset:128 nt
	global_store_dword v[120:121], v188, off offset:128 nt
	v_addc_co_u32_e32 v105, vcc, 0, v101, vcc
	v_add_co_u32_e32 v106, vcc, s75, v100
	v_lshl_add_u64 v[98:99], s[56:57], 0, v[98:99]
	s_nop 0
	v_addc_co_u32_e32 v107, vcc, 0, v101, vcc
	s_waitcnt vmcnt(15)
	v_fmac_f32_e32 v189, v108, v0
	s_waitcnt vmcnt(14)
	v_fmac_f32_e32 v190, v110, v0
	s_waitcnt vmcnt(13)
	v_fmac_f32_e32 v172, v109, v0
	s_waitcnt vmcnt(12)
	v_fmac_f32_e32 v173, v111, v0
	global_store_dword v[166:167], v189, off offset:128 nt
	global_store_dword v[122:123], v172, off offset:128 nt
	global_store_dword v[168:169], v190, off offset:128 nt
	global_store_dword v[124:125], v173, off offset:128 nt
	s_waitcnt vmcnt(15)
	v_fmac_f32_e32 v174, v112, v0
	s_waitcnt vmcnt(14)
	v_fmac_f32_e32 v175, v113, v0
	global_store_dword v[170:171], v174, off offset:128 nt
	global_store_dword v[126:127], v175, off offset:128 nt
	global_load_dword v0, v[140:141], off
	s_nop 0
	global_load_dword v126, v[100:101], off nt
	global_load_dword v127, v[102:103], off offset:-4096 nt
	v_add_co_u32_e32 v108, vcc, s95, v100
	s_waitcnt vmcnt(1)
	v_fmac_f32_e32 v126, v82, v0
	v_addc_co_u32_e32 v109, vcc, 0, v101, vcc
	global_load_dword v128, v[102:103], off nt
	global_load_dword v129, v[106:107], off offset:-4096 nt
	global_load_dword v135, v[106:107], off nt
	global_load_dword v139, v[108:109], off offset:-4096 nt
	global_load_dword v142, v[108:109], off nt
	global_load_dword v143, v[104:105], off nt
	v_add_co_u32_e32 v110, vcc, s31, v100
	s_waitcnt vmcnt(6)
	v_fmac_f32_e32 v127, v83, v0
	v_addc_co_u32_e32 v111, vcc, 0, v101, vcc
	v_add_co_u32_e32 v112, vcc, s36, v100
	global_load_dword v159, v[110:111], off offset:-4096 nt
	global_load_dword v160, v[110:111], off nt
	v_addc_co_u32_e32 v113, vcc, 0, v101, vcc
	v_add_co_u32_e32 v116, vcc, s37, v100
	global_load_dword v161, v[112:113], off offset:-4096 nt
	global_load_dword v162, v[112:113], off nt
	v_addc_co_u32_e32 v117, vcc, 0, v101, vcc
	v_add_co_u32_e32 v118, vcc, s39, v100
	global_load_dword v163, v[116:117], off offset:-4096 nt
	global_load_dword v164, v[116:117], off nt
	v_addc_co_u32_e32 v119, vcc, 0, v101, vcc
	global_load_dword v165, v[118:119], off offset:-4096 nt
	global_load_dword v166, v[118:119], off nt
	v_add_co_u32_e32 v120, vcc, s28, v100
	global_store_dword v[98:99], v126, off nt
	s_nop 0
	v_addc_co_u32_e32 v121, vcc, 0, v101, vcc
	v_add_co_u32_e32 v122, vcc, s94, v100
	s_waitcnt vmcnt(14)
	v_fmac_f32_e32 v128, v84, v0
	v_addc_co_u32_e32 v123, vcc, 0, v101, vcc
	v_add_co_u32_e32 v124, vcc, s87, v100
	s_waitcnt vmcnt(9)
	v_fmac_f32_e32 v143, v85, v0
	v_addc_co_u32_e32 v125, vcc, 0, v101, vcc
	v_add_co_u32_e32 v82, vcc, s29, v98
	v_fmac_f32_e32 v129, v86, v0
	s_nop 0
	v_addc_co_u32_e32 v83, vcc, 0, v99, vcc
	v_add_co_u32_e32 v84, vcc, s73, v98
	global_store_dword v[82:83], v127, off offset:-4096 nt
	s_nop 0
	v_addc_co_u32_e32 v85, vcc, 0, v99, vcc
	v_add_co_u32_e32 v126, vcc, s75, v98
	v_fmac_f32_e32 v135, v87, v0
	s_nop 0
	v_addc_co_u32_e32 v127, vcc, 0, v99, vcc
	v_add_co_u32_e32 v86, vcc, s95, v98
	v_fmac_f32_e32 v139, v88, v0
	s_nop 0
	v_addc_co_u32_e32 v87, vcc, 0, v99, vcc
	v_add_co_u32_e32 v88, vcc, s31, v98
	v_fmac_f32_e32 v142, v89, v0
	s_nop 0
	v_addc_co_u32_e32 v89, vcc, 0, v99, vcc
	s_waitcnt vmcnt(9)
	v_fmac_f32_e32 v159, v90, v0
	v_add_co_u32_e32 v90, vcc, s36, v98
	s_waitcnt vmcnt(8)
	v_fmac_f32_e32 v160, v91, v0
	v_addc_co_u32_e32 v91, vcc, 0, v99, vcc
	s_waitcnt vmcnt(7)
	v_fmac_f32_e32 v161, v92, v0
	v_add_co_u32_e32 v92, vcc, s37, v98
	s_waitcnt vmcnt(6)
	v_fmac_f32_e32 v162, v93, v0
	v_addc_co_u32_e32 v93, vcc, 0, v99, vcc
	s_waitcnt vmcnt(5)
	v_fmac_f32_e32 v163, v94, v0
	v_add_co_u32_e32 v94, vcc, s39, v98
	s_waitcnt vmcnt(4)
	v_fmac_f32_e32 v164, v95, v0
	s_waitcnt vmcnt(3)
	v_fmac_f32_e32 v165, v96, v0
	v_addc_co_u32_e32 v95, vcc, 0, v99, vcc
	s_waitcnt vmcnt(2)
	v_fmac_f32_e32 v166, v97, v0
	global_store_dword v[82:83], v128, off nt
	global_store_dword v[84:85], v143, off nt
	global_store_dword v[126:127], v129, off offset:-4096 nt
	global_store_dword v[126:127], v135, off nt
	global_store_dword v[86:87], v139, off offset:-4096 nt
	global_store_dword v[86:87], v142, off nt
	global_store_dword v[88:89], v159, off offset:-4096 nt
	global_store_dword v[88:89], v160, off nt
	global_store_dword v[90:91], v161, off offset:-4096 nt
	global_store_dword v[90:91], v162, off nt
	global_store_dword v[92:93], v163, off offset:-4096 nt
	global_store_dword v[92:93], v164, off nt
	global_store_dword v[94:95], v165, off offset:-4096 nt
	global_store_dword v[94:95], v166, off nt
	global_load_dword v0, v[114:115], off
	global_load_dword v128, v[100:101], off offset:128 nt
	v_add_co_u32_e32 v96, vcc, s0, v100
	global_load_dword v120, v[120:121], off offset:128 nt
	s_nop 0
	global_load_dword v121, v[102:103], off offset:128 nt
	global_load_dword v129, v[104:105], off offset:128 nt
	s_nop 0
	global_load_dword v122, v[122:123], off offset:128 nt
	v_addc_co_u32_e32 v97, vcc, 0, v101, vcc
	v_add_co_u32_e32 v102, vcc, s72, v100
	global_load_dword v123, v[106:107], off offset:128 nt
	global_load_dword v135, v[108:109], off offset:128 nt
	s_nop 0
	global_load_dword v124, v[124:125], off offset:128 nt
	s_nop 0
	global_load_dword v125, v[96:97], off offset:128 nt
	v_addc_co_u32_e32 v103, vcc, 0, v101, vcc
	v_add_co_u32_e32 v96, vcc, s1, v100
	s_waitcnt vmcnt(8)
	v_fmac_f32_e32 v128, v66, v0
	v_addc_co_u32_e32 v97, vcc, 0, v101, vcc
	global_load_dword v139, v[110:111], off offset:128 nt
	s_nop 0
	global_load_dword v112, v[112:113], off offset:128 nt
	s_nop 0
	global_load_dword v113, v[102:103], off offset:128 nt
	global_load_dword v142, v[96:97], off offset:128 nt
	v_add_co_u32_e32 v96, vcc, s38, v100
	v_or_b32_e32 v66, 64, v138
	s_nop 0
	v_addc_co_u32_e32 v97, vcc, 0, v101, vcc
	global_load_dword v116, v[116:117], off offset:128 nt
	s_nop 0
	global_load_dword v117, v[118:119], off offset:128 nt
	s_nop 0
	global_load_dword v118, v[96:97], off offset:128 nt
	v_add_co_u32_e32 v96, vcc, s28, v98
	s_waitcnt vmcnt(14)
	v_fmac_f32_e32 v120, v67, v0
	v_addc_co_u32_e32 v97, vcc, 0, v99, vcc
	v_add_co_u32_e32 v100, vcc, s94, v98
	v_ashrrev_i32_e32 v67, 31, v66
	s_nop 0
	v_addc_co_u32_e32 v101, vcc, 0, v99, vcc
	v_add_co_u32_e32 v102, vcc, s87, v98
	v_lshlrev_b64 v[66:67], 10, v[66:67]
	s_nop 0
	v_addc_co_u32_e32 v103, vcc, 0, v99, vcc
	v_add_co_u32_e32 v104, vcc, s0, v98
	v_lshl_add_u64 v[66:67], v[66:67], 0, v[136:137]
	s_nop 0
	v_addc_co_u32_e32 v105, vcc, 0, v99, vcc
	v_add_co_u32_e32 v106, vcc, s72, v98
	v_lshlrev_b64 v[66:67], 2, v[66:67]
	s_nop 0
	v_addc_co_u32_e32 v107, vcc, 0, v99, vcc
	v_add_co_u32_e32 v108, vcc, s1, v98
	s_waitcnt vmcnt(13)
	v_fmac_f32_e32 v121, v68, v0
	v_addc_co_u32_e32 v109, vcc, 0, v99, vcc
	v_add_co_u32_e32 v110, vcc, s38, v98
	s_waitcnt vmcnt(12)
	v_fmac_f32_e32 v129, v69, v0
	v_addc_co_u32_e32 v111, vcc, 0, v99, vcc
	v_lshl_add_u64 v[68:69], s[98:99], 0, v[66:67]
	s_waitcnt vmcnt(11)
	v_fmac_f32_e32 v122, v70, v0
	v_add_co_u32_e32 v70, vcc, s29, v68
	s_waitcnt vmcnt(10)
	v_fmac_f32_e32 v123, v71, v0
	v_addc_co_u32_e32 v71, vcc, 0, v69, vcc
	s_waitcnt vmcnt(8)
	v_fmac_f32_e32 v124, v72, v0
	v_fmac_f32_e32 v135, v73, v0
	s_waitcnt vmcnt(7)
	v_fmac_f32_e32 v125, v74, v0
	v_add_co_u32_e32 v72, vcc, s73, v68
	global_store_dword v[98:99], v128, off offset:128 nt
	global_store_dword v[96:97], v120, off offset:128 nt
	global_store_dword v[82:83], v121, off offset:128 nt
	global_store_dword v[84:85], v129, off offset:128 nt
	global_store_dword v[100:101], v122, off offset:128 nt
	global_store_dword v[126:127], v123, off offset:128 nt
	global_store_dword v[102:103], v124, off offset:128 nt
	global_store_dword v[86:87], v135, off offset:128 nt
	global_store_dword v[104:105], v125, off offset:128 nt
	v_addc_co_u32_e32 v73, vcc, 0, v69, vcc
	v_add_co_u32_e32 v74, vcc, s75, v68
	v_lshl_add_u64 v[66:67], s[56:57], 0, v[66:67]
	s_waitcnt vmcnt(15)
	v_fmac_f32_e32 v139, v75, v0
	s_waitcnt vmcnt(14)
	v_fmac_f32_e32 v112, v77, v0
	s_waitcnt vmcnt(13)
	v_fmac_f32_e32 v113, v76, v0
	s_waitcnt vmcnt(12)
	v_fmac_f32_e32 v142, v78, v0
	global_store_dword v[88:89], v139, off offset:128 nt
	global_store_dword v[106:107], v113, off offset:128 nt
	global_store_dword v[90:91], v112, off offset:128 nt
	s_waitcnt vmcnt(14)
	v_fmac_f32_e32 v116, v79, v0
	s_waitcnt vmcnt(13)
	v_fmac_f32_e32 v117, v81, v0
	s_waitcnt vmcnt(12)
	v_fmac_f32_e32 v118, v80, v0
	global_store_dword v[108:109], v142, off offset:128 nt
	global_store_dword v[92:93], v116, off offset:128 nt
	global_store_dword v[110:111], v118, off offset:128 nt
	global_store_dword v[94:95], v117, off offset:128 nt
	global_load_dword v0, v[140:141], off
	s_nop 0
	global_load_dword v92, v[68:69], off nt
	global_load_dword v93, v[70:71], off offset:-4096 nt
	v_addc_co_u32_e32 v75, vcc, 0, v69, vcc
	v_add_co_u32_e32 v76, vcc, s95, v68
	s_waitcnt vmcnt(1)
	v_fmac_f32_e32 v92, v50, v0
	v_addc_co_u32_e32 v77, vcc, 0, v69, vcc
	global_load_dword v94, v[70:71], off nt
	global_load_dword v95, v[74:75], off offset:-4096 nt
	global_load_dword v96, v[74:75], off nt
	global_load_dword v97, v[76:77], off offset:-4096 nt
	global_load_dword v98, v[76:77], off nt
	global_load_dword v99, v[72:73], off nt
	v_add_co_u32_e32 v78, vcc, s31, v68
	s_waitcnt vmcnt(6)
	v_fmac_f32_e32 v93, v51, v0
	v_addc_co_u32_e32 v79, vcc, 0, v69, vcc
	v_add_co_u32_e32 v80, vcc, s36, v68
	global_load_dword v100, v[78:79], off offset:-4096 nt
	global_load_dword v101, v[78:79], off nt
	v_addc_co_u32_e32 v81, vcc, 0, v69, vcc
	v_add_co_u32_e32 v82, vcc, s37, v68
	global_load_dword v102, v[80:81], off offset:-4096 nt
	global_load_dword v103, v[80:81], off nt
	v_addc_co_u32_e32 v83, vcc, 0, v69, vcc
	v_add_co_u32_e32 v84, vcc, s39, v68
	global_load_dword v104, v[82:83], off offset:-4096 nt
	global_load_dword v105, v[82:83], off nt
	v_addc_co_u32_e32 v85, vcc, 0, v69, vcc
	global_load_dword v106, v[84:85], off offset:-4096 nt
	global_load_dword v107, v[84:85], off nt
	v_add_co_u32_e32 v86, vcc, s28, v68
	global_store_dword v[66:67], v92, off nt
	s_nop 0
	v_addc_co_u32_e32 v87, vcc, 0, v69, vcc
	v_add_co_u32_e32 v88, vcc, s94, v68
	s_waitcnt vmcnt(14)
	v_fmac_f32_e32 v94, v52, v0
	v_addc_co_u32_e32 v89, vcc, 0, v69, vcc
	v_add_co_u32_e32 v90, vcc, s87, v68
	s_waitcnt vmcnt(9)
	v_fmac_f32_e32 v99, v53, v0
	v_addc_co_u32_e32 v91, vcc, 0, v69, vcc
	v_add_co_u32_e32 v50, vcc, s29, v66
	v_fmac_f32_e32 v95, v54, v0
	s_nop 0
	v_addc_co_u32_e32 v51, vcc, 0, v67, vcc
	v_add_co_u32_e32 v52, vcc, s73, v66
	global_store_dword v[50:51], v93, off offset:-4096 nt
	s_nop 0
	v_addc_co_u32_e32 v53, vcc, 0, v67, vcc
	v_add_co_u32_e32 v92, vcc, s75, v66
	v_fmac_f32_e32 v96, v55, v0
	s_nop 0
	v_addc_co_u32_e32 v93, vcc, 0, v67, vcc
	v_add_co_u32_e32 v54, vcc, s95, v66
	v_fmac_f32_e32 v97, v56, v0
	s_nop 0
	v_addc_co_u32_e32 v55, vcc, 0, v67, vcc
	v_add_co_u32_e32 v56, vcc, s31, v66
	v_fmac_f32_e32 v98, v57, v0
	s_nop 0
	v_addc_co_u32_e32 v57, vcc, 0, v67, vcc
	s_waitcnt vmcnt(9)
	v_fmac_f32_e32 v100, v58, v0
	v_add_co_u32_e32 v58, vcc, s36, v66
	s_waitcnt vmcnt(8)
	v_fmac_f32_e32 v101, v59, v0
	v_addc_co_u32_e32 v59, vcc, 0, v67, vcc
	s_waitcnt vmcnt(7)
	v_fmac_f32_e32 v102, v60, v0
	v_add_co_u32_e32 v60, vcc, s37, v66
	s_waitcnt vmcnt(6)
	v_fmac_f32_e32 v103, v61, v0
	v_addc_co_u32_e32 v61, vcc, 0, v67, vcc
	s_waitcnt vmcnt(5)
	v_fmac_f32_e32 v104, v62, v0
	v_add_co_u32_e32 v62, vcc, s39, v66
	s_waitcnt vmcnt(4)
	v_fmac_f32_e32 v105, v63, v0
	s_waitcnt vmcnt(3)
	v_fmac_f32_e32 v106, v64, v0
	v_addc_co_u32_e32 v63, vcc, 0, v67, vcc
	s_waitcnt vmcnt(2)
	v_fmac_f32_e32 v107, v65, v0
	global_store_dword v[50:51], v94, off nt
	global_store_dword v[52:53], v99, off nt
	global_store_dword v[92:93], v95, off offset:-4096 nt
	global_store_dword v[92:93], v96, off nt
	global_store_dword v[54:55], v97, off offset:-4096 nt
	global_store_dword v[54:55], v98, off nt
	global_store_dword v[56:57], v100, off offset:-4096 nt
	global_store_dword v[56:57], v101, off nt
	global_store_dword v[58:59], v102, off offset:-4096 nt
	global_store_dword v[58:59], v103, off nt
	global_store_dword v[60:61], v104, off offset:-4096 nt
	global_store_dword v[60:61], v105, off nt
	global_store_dword v[62:63], v106, off offset:-4096 nt
	global_store_dword v[62:63], v107, off nt
	global_load_dword v0, v[114:115], off
	global_load_dword v94, v[68:69], off offset:128 nt
	v_add_co_u32_e32 v64, vcc, s0, v68
	global_load_dword v86, v[86:87], off offset:128 nt
	s_nop 0
	global_load_dword v87, v[70:71], off offset:128 nt
	global_load_dword v95, v[72:73], off offset:128 nt
	s_nop 0
	global_load_dword v88, v[88:89], off offset:128 nt
	v_addc_co_u32_e32 v65, vcc, 0, v69, vcc
	v_add_co_u32_e32 v70, vcc, s72, v68
	global_load_dword v89, v[74:75], off offset:128 nt
	global_load_dword v96, v[76:77], off offset:128 nt
	s_nop 0
	global_load_dword v90, v[90:91], off offset:128 nt
	s_nop 0
	global_load_dword v91, v[64:65], off offset:128 nt
	v_addc_co_u32_e32 v71, vcc, 0, v69, vcc
	v_add_co_u32_e32 v64, vcc, s1, v68
	s_waitcnt vmcnt(8)
	v_fmac_f32_e32 v94, v34, v0
	v_addc_co_u32_e32 v65, vcc, 0, v69, vcc
	global_load_dword v97, v[78:79], off offset:128 nt
	s_nop 0
	global_load_dword v80, v[80:81], off offset:128 nt
	s_nop 0
	global_load_dword v81, v[70:71], off offset:128 nt
	global_load_dword v98, v[64:65], off offset:128 nt
	v_add_co_u32_e32 v64, vcc, s38, v68
	v_or_b32_e32 v34, 0x60, v138
	s_nop 0
	v_addc_co_u32_e32 v65, vcc, 0, v69, vcc
	global_load_dword v82, v[82:83], off offset:128 nt
	s_nop 0
	global_load_dword v83, v[84:85], off offset:128 nt
	s_nop 0
	global_load_dword v84, v[64:65], off offset:128 nt
	v_add_co_u32_e32 v64, vcc, s28, v66
	s_waitcnt vmcnt(14)
	v_fmac_f32_e32 v86, v35, v0
	v_addc_co_u32_e32 v65, vcc, 0, v67, vcc
	v_add_co_u32_e32 v68, vcc, s94, v66
	v_ashrrev_i32_e32 v35, 31, v34
	s_nop 0
	v_addc_co_u32_e32 v69, vcc, 0, v67, vcc
	v_add_co_u32_e32 v70, vcc, s87, v66
	v_lshlrev_b64 v[34:35], 10, v[34:35]
	s_nop 0
	v_addc_co_u32_e32 v71, vcc, 0, v67, vcc
	v_add_co_u32_e32 v72, vcc, s0, v66
	v_lshl_add_u64 v[34:35], v[34:35], 0, v[136:137]
	s_nop 0
	v_addc_co_u32_e32 v73, vcc, 0, v67, vcc
	v_add_co_u32_e32 v74, vcc, s72, v66
	s_waitcnt vmcnt(13)
	v_fmac_f32_e32 v87, v36, v0
	v_addc_co_u32_e32 v75, vcc, 0, v67, vcc
	v_add_co_u32_e32 v76, vcc, s1, v66
	s_waitcnt vmcnt(12)
	v_fmac_f32_e32 v95, v37, v0
	v_addc_co_u32_e32 v77, vcc, 0, v67, vcc
	v_add_co_u32_e32 v78, vcc, s38, v66
	v_lshlrev_b64 v[36:37], 2, v[34:35]
	s_nop 0
	v_addc_co_u32_e32 v79, vcc, 0, v67, vcc
	v_lshl_add_u64 v[34:35], s[98:99], 0, v[36:37]
	s_waitcnt vmcnt(11)
	v_fmac_f32_e32 v88, v38, v0
	v_add_co_u32_e32 v38, vcc, s29, v34
	s_waitcnt vmcnt(10)
	v_fmac_f32_e32 v89, v39, v0
	v_addc_co_u32_e32 v39, vcc, 0, v35, vcc
	s_waitcnt vmcnt(8)
	v_fmac_f32_e32 v90, v40, v0
	v_fmac_f32_e32 v96, v41, v0
	s_waitcnt vmcnt(7)
	v_fmac_f32_e32 v91, v42, v0
	v_add_co_u32_e32 v40, vcc, s73, v34
	global_store_dword v[66:67], v94, off offset:128 nt
	global_store_dword v[64:65], v86, off offset:128 nt
	global_store_dword v[50:51], v87, off offset:128 nt
	global_store_dword v[52:53], v95, off offset:128 nt
	global_store_dword v[68:69], v88, off offset:128 nt
	global_store_dword v[92:93], v89, off offset:128 nt
	global_store_dword v[70:71], v90, off offset:128 nt
	global_store_dword v[54:55], v96, off offset:128 nt
	global_store_dword v[72:73], v91, off offset:128 nt
	v_addc_co_u32_e32 v41, vcc, 0, v35, vcc
	v_add_co_u32_e32 v42, vcc, s75, v34
	v_lshl_add_u64 v[36:37], s[56:57], 0, v[36:37]
	s_waitcnt vmcnt(15)
	v_fmac_f32_e32 v97, v43, v0
	s_waitcnt vmcnt(14)
	v_fmac_f32_e32 v80, v45, v0
	s_waitcnt vmcnt(13)
	v_fmac_f32_e32 v81, v44, v0
	s_waitcnt vmcnt(12)
	v_fmac_f32_e32 v98, v46, v0
	global_store_dword v[56:57], v97, off offset:128 nt
	global_store_dword v[74:75], v81, off offset:128 nt
	global_store_dword v[58:59], v80, off offset:128 nt
	s_waitcnt vmcnt(14)
	v_fmac_f32_e32 v82, v47, v0
	s_waitcnt vmcnt(13)
	v_fmac_f32_e32 v83, v49, v0
	s_waitcnt vmcnt(12)
	v_fmac_f32_e32 v84, v48, v0
	global_store_dword v[76:77], v98, off offset:128 nt
	global_store_dword v[60:61], v82, off offset:128 nt
	global_store_dword v[78:79], v84, off offset:128 nt
	global_store_dword v[62:63], v83, off offset:128 nt
	global_load_dword v0, v[140:141], off
	s_nop 0
	global_load_dword v60, v[34:35], off nt
	global_load_dword v61, v[38:39], off offset:-4096 nt
	v_addc_co_u32_e32 v43, vcc, 0, v35, vcc
	v_add_co_u32_e32 v44, vcc, s95, v34
	s_waitcnt vmcnt(1)
	v_fmac_f32_e32 v60, v18, v0
	v_addc_co_u32_e32 v45, vcc, 0, v35, vcc
	global_load_dword v62, v[38:39], off nt
	global_load_dword v63, v[42:43], off offset:-4096 nt
	global_load_dword v64, v[42:43], off nt
	global_load_dword v65, v[44:45], off offset:-4096 nt
	global_load_dword v66, v[44:45], off nt
	global_load_dword v67, v[40:41], off nt
	v_add_co_u32_e32 v46, vcc, s31, v34
	s_waitcnt vmcnt(6)
	v_fmac_f32_e32 v61, v19, v0
	v_addc_co_u32_e32 v47, vcc, 0, v35, vcc
	v_add_co_u32_e32 v48, vcc, s36, v34
	global_load_dword v68, v[46:47], off offset:-4096 nt
	global_load_dword v69, v[46:47], off nt
	v_addc_co_u32_e32 v49, vcc, 0, v35, vcc
	v_add_co_u32_e32 v50, vcc, s37, v34
	global_load_dword v70, v[48:49], off offset:-4096 nt
	global_load_dword v71, v[48:49], off nt
	v_addc_co_u32_e32 v51, vcc, 0, v35, vcc
	v_add_co_u32_e32 v52, vcc, s39, v34
	global_load_dword v72, v[50:51], off offset:-4096 nt
	global_load_dword v73, v[50:51], off nt
	v_addc_co_u32_e32 v53, vcc, 0, v35, vcc
	global_load_dword v74, v[52:53], off offset:-4096 nt
	global_load_dword v75, v[52:53], off nt
	v_add_co_u32_e32 v54, vcc, s28, v34
	global_store_dword v[36:37], v60, off nt
	s_nop 0
	v_addc_co_u32_e32 v55, vcc, 0, v35, vcc
	v_add_co_u32_e32 v56, vcc, s94, v34
	s_waitcnt vmcnt(14)
	v_fmac_f32_e32 v62, v20, v0
	v_addc_co_u32_e32 v57, vcc, 0, v35, vcc
	v_add_co_u32_e32 v58, vcc, s87, v34
	s_waitcnt vmcnt(9)
	v_fmac_f32_e32 v67, v21, v0
	v_addc_co_u32_e32 v59, vcc, 0, v35, vcc
	v_add_co_u32_e32 v18, vcc, s29, v36
	v_fmac_f32_e32 v63, v22, v0
	s_nop 0
	v_addc_co_u32_e32 v19, vcc, 0, v37, vcc
	v_add_co_u32_e32 v20, vcc, s73, v36
	global_store_dword v[18:19], v61, off offset:-4096 nt
	s_nop 0
	v_addc_co_u32_e32 v21, vcc, 0, v37, vcc
	v_add_co_u32_e32 v60, vcc, s75, v36
	v_fmac_f32_e32 v64, v23, v0
	s_nop 0
	v_addc_co_u32_e32 v61, vcc, 0, v37, vcc
	v_add_co_u32_e32 v22, vcc, s95, v36
	v_fmac_f32_e32 v65, v24, v0
	s_nop 0
	v_addc_co_u32_e32 v23, vcc, 0, v37, vcc
	v_add_co_u32_e32 v24, vcc, s31, v36
	v_fmac_f32_e32 v66, v25, v0
	s_nop 0
	v_addc_co_u32_e32 v25, vcc, 0, v37, vcc
	s_waitcnt vmcnt(9)
	v_fmac_f32_e32 v68, v26, v0
	v_add_co_u32_e32 v26, vcc, s36, v36
	s_waitcnt vmcnt(8)
	v_fmac_f32_e32 v69, v27, v0
	v_addc_co_u32_e32 v27, vcc, 0, v37, vcc
	s_waitcnt vmcnt(7)
	v_fmac_f32_e32 v70, v28, v0
	v_add_co_u32_e32 v28, vcc, s37, v36
	s_waitcnt vmcnt(6)
	v_fmac_f32_e32 v71, v29, v0
	v_addc_co_u32_e32 v29, vcc, 0, v37, vcc
	s_waitcnt vmcnt(5)
	v_fmac_f32_e32 v72, v30, v0
	v_add_co_u32_e32 v30, vcc, s39, v36
	s_waitcnt vmcnt(4)
	v_fmac_f32_e32 v73, v31, v0
	v_addc_co_u32_e32 v31, vcc, 0, v37, vcc
	s_waitcnt vmcnt(3)
	v_fmac_f32_e32 v74, v32, v0
	s_waitcnt vmcnt(2)
	v_fmac_f32_e32 v75, v33, v0
	v_add_co_u32_e32 v32, vcc, s0, v34
	global_store_dword v[18:19], v62, off nt
	global_store_dword v[20:21], v67, off nt
	global_store_dword v[60:61], v63, off offset:-4096 nt
	global_store_dword v[60:61], v64, off nt
	global_store_dword v[22:23], v65, off offset:-4096 nt
	global_store_dword v[22:23], v66, off nt
	global_store_dword v[24:25], v68, off offset:-4096 nt
	global_store_dword v[24:25], v69, off nt
	global_store_dword v[26:27], v70, off offset:-4096 nt
	global_store_dword v[26:27], v71, off nt
	global_store_dword v[28:29], v72, off offset:-4096 nt
	global_store_dword v[28:29], v73, off nt
	global_store_dword v[30:31], v74, off offset:-4096 nt
	global_store_dword v[30:31], v75, off nt
	v_addc_co_u32_e32 v33, vcc, 0, v35, vcc
	global_load_dword v0, v[114:115], off
	global_load_dword v62, v[34:35], off offset:128 nt
	s_nop 0
	global_load_dword v54, v[54:55], off offset:128 nt
	s_nop 0
	global_load_dword v55, v[38:39], off offset:128 nt
	global_load_dword v63, v[40:41], off offset:128 nt
	s_nop 0
	global_load_dword v56, v[56:57], off offset:128 nt
	v_add_co_u32_e32 v38, vcc, s72, v34
	global_load_dword v57, v[42:43], off offset:128 nt
	global_load_dword v64, v[44:45], off offset:128 nt
	s_nop 0
	global_load_dword v58, v[58:59], off offset:128 nt
	s_nop 0
	global_load_dword v59, v[32:33], off offset:128 nt
	v_addc_co_u32_e32 v39, vcc, 0, v35, vcc
	v_add_co_u32_e32 v32, vcc, s1, v34
	s_waitcnt vmcnt(7)
	v_fmac_f32_e32 v54, v3, v0
	v_addc_co_u32_e32 v33, vcc, 0, v35, vcc
	global_load_dword v65, v[46:47], off offset:128 nt
	s_nop 0
	global_load_dword v48, v[48:49], off offset:128 nt
	s_nop 0
	global_load_dword v49, v[38:39], off offset:128 nt
	global_load_dword v66, v[32:33], off offset:128 nt
	v_add_co_u32_e32 v32, vcc, s38, v34
	v_fmac_f32_e32 v62, v2, v0
	s_nop 0
	v_addc_co_u32_e32 v33, vcc, 0, v35, vcc
	global_load_dword v50, v[50:51], off offset:128 nt
	s_nop 0
	global_load_dword v51, v[52:53], off offset:128 nt
	s_nop 0
	global_load_dword v52, v[32:33], off offset:128 nt
	v_add_co_u32_e32 v32, vcc, s28, v36
	s_waitcnt vmcnt(13)
	v_fmac_f32_e32 v55, v4, v0
	v_addc_co_u32_e32 v33, vcc, 0, v37, vcc
	v_add_co_u32_e32 v34, vcc, s94, v36
	s_waitcnt vmcnt(12)
	v_fmac_f32_e32 v63, v5, v0
	v_addc_co_u32_e32 v35, vcc, 0, v37, vcc
	v_add_co_u32_e32 v38, vcc, s87, v36
	s_waitcnt vmcnt(11)
	v_fmac_f32_e32 v56, v6, v0
	v_addc_co_u32_e32 v39, vcc, 0, v37, vcc
	v_add_co_u32_e32 v40, vcc, s0, v36
	s_waitcnt vmcnt(10)
	v_fmac_f32_e32 v57, v7, v0
	v_addc_co_u32_e32 v41, vcc, 0, v37, vcc
	v_add_co_u32_e32 v42, vcc, s72, v36
	s_waitcnt vmcnt(8)
	v_fmac_f32_e32 v58, v8, v0
	v_addc_co_u32_e32 v43, vcc, 0, v37, vcc
	v_add_co_u32_e32 v44, vcc, s1, v36
	v_fmac_f32_e32 v64, v9, v0
	s_nop 0
	v_addc_co_u32_e32 v45, vcc, 0, v37, vcc
	v_add_co_u32_e32 v46, vcc, s38, v36
	s_waitcnt vmcnt(7)
	v_fmac_f32_e32 v59, v10, v0
	v_addc_co_u32_e32 v47, vcc, 0, v37, vcc
	global_store_dword v[36:37], v62, off offset:128 nt
	global_store_dword v[32:33], v54, off offset:128 nt
	global_store_dword v[18:19], v55, off offset:128 nt
	global_store_dword v[20:21], v63, off offset:128 nt
	global_store_dword v[34:35], v56, off offset:128 nt
	global_store_dword v[60:61], v57, off offset:128 nt
	global_store_dword v[38:39], v58, off offset:128 nt
	global_store_dword v[22:23], v64, off offset:128 nt
	global_store_dword v[40:41], v59, off offset:128 nt
	s_waitcnt vmcnt(15)
	v_fmac_f32_e32 v65, v11, v0
	s_waitcnt vmcnt(14)
	v_fmac_f32_e32 v48, v13, v0
	s_waitcnt vmcnt(13)
	v_fmac_f32_e32 v49, v12, v0
	s_waitcnt vmcnt(12)
	v_fmac_f32_e32 v66, v14, v0
	global_store_dword v[24:25], v65, off offset:128 nt
	global_store_dword v[42:43], v49, off offset:128 nt
	global_store_dword v[26:27], v48, off offset:128 nt
	s_waitcnt vmcnt(14)
	v_fmac_f32_e32 v50, v15, v0
	s_waitcnt vmcnt(13)
	v_fmac_f32_e32 v51, v17, v0
	s_waitcnt vmcnt(12)
	v_fmac_f32_e32 v52, v16, v0
	global_store_dword v[44:45], v66, off offset:128 nt
	global_store_dword v[28:29], v50, off offset:128 nt
	global_store_dword v[46:47], v52, off offset:128 nt
	global_store_dword v[30:31], v51, off offset:128 nt
	s_cbranch_scc0 .LBB0_52

.LBB0_220:
	s_cmp_gt_i32 s7, 0
	s_waitcnt vmcnt(6)
	s_cselect_b32 s8, -1, 2
	s_mul_i32 s9, s7, 0x6000
	s_waitcnt lgkmcnt(0)
	s_add_i32 s8, s8, s7
	v_add_u32_e32 v139, s9, v224
	v_add_u32_e32 v0, s9, v223
	s_mulk_i32 s8, 0x6000
	v_add_u32_e32 v154, v139, v228
	s_barrier
	v_lshl_add_u64 v[170:171], v[144:145], 0, s[2:3]
	v_add_u32_e32 v141, s8, v221
	v_lshl_add_u64 v[174:175], v[142:143], 0, s[2:3]
	v_add_u32_e32 v182, s8, v222
	v_add_u32_e32 v166, v0, v228
	ds_read_b128 v[146:149], v166
	ds_read_b128 v[150:153], v154
	ds_read_b128 v[154:157], v154 offset:2048
	v_lshl_add_u64 v[172:173], v[170:171], 0, s[88:89]
	v_lshl_add_u64 v[176:177], v[174:175], 0, s[88:89]
	v_add_u32_e32 v183, 0x4000, v182
	v_lshl_add_u64 v[178:179], v[170:171], 0, s[90:91]
	v_add_u32_e32 v184, 0x400, v141
	v_lshl_add_u64 v[180:181], v[170:171], 0, s[78:79]
	v_add_u32_e32 v185, 0x800, v141
	ds_read_b128 v[158:161], v166 offset:2048
	ds_read_b128 v[162:165], v166 offset:4096
	ds_read_b128 v[166:169], v166 offset:6144
	s_waitcnt lgkmcnt(3)
	s_setprio 1
	v_mfma_f32_32x32x16_bf16 v[114:129], v[146:149], v[150:153], v[114:129]
	v_mfma_f32_32x32x16_bf16 v[98:113], v[146:149], v[154:157], v[98:113]
	v_readfirstlane_b32 s8, v141
	s_mov_b32 m0, s8
	s_nop 0
	global_load_lds_dwordx4 v[172:173], off
	s_waitcnt lgkmcnt(2)
	v_mfma_f32_32x32x16_bf16 v[82:97], v[158:161], v[150:153], v[82:97]
	v_mfma_f32_32x32x16_bf16 v[66:81], v[158:161], v[154:157], v[66:81]
	v_readfirstlane_b32 s8, v184
	s_mov_b32 m0, s8
	s_nop 0
	global_load_lds_dwordx4 v[178:179], off
	s_waitcnt lgkmcnt(1)
	v_mfma_f32_32x32x16_bf16 v[50:65], v[162:165], v[150:153], v[50:65]
	v_mfma_f32_32x32x16_bf16 v[34:49], v[162:165], v[154:157], v[34:49]
	v_readfirstlane_b32 s8, v185
	s_mov_b32 m0, s8
	s_nop 0
	global_load_lds_dwordx4 v[180:181], off
	s_waitcnt lgkmcnt(0)
	v_mfma_f32_32x32x16_bf16 v[18:33], v[166:169], v[150:153], v[18:33]
	v_mfma_f32_32x32x16_bf16 v[2:17], v[166:169], v[154:157], v[2:17]
	s_setprio 0
	v_add_u32_e32 v0, v0, v229
	v_add_u32_e32 v139, v139, v229
	ds_read_b128 v[146:149], v0
	ds_read_b128 v[150:153], v139
	ds_read_b128 v[154:157], v139 offset:2048
	ds_read_b128 v[158:161], v0 offset:2048
	ds_read_b128 v[162:165], v0 offset:4096
	ds_read_b128 v[166:169], v0 offset:6144
	s_waitcnt lgkmcnt(3)
	s_setprio 1
	v_mfma_f32_32x32x16_bf16 v[114:129], v[146:149], v[150:153], v[114:129]
	v_mfma_f32_32x32x16_bf16 v[98:113], v[146:149], v[154:157], v[98:113]
	v_add_u32_e32 v0, 0xc00, v141
	v_lshl_add_u64 v[146:147], v[170:171], 0, s[76:77]
	v_readfirstlane_b32 s8, v0
	s_mov_b32 m0, s8
	s_nop 0
	global_load_lds_dwordx4 v[146:147], off
	s_waitcnt lgkmcnt(2)
	v_mfma_f32_32x32x16_bf16 v[82:97], v[158:161], v[150:153], v[82:97]
	v_mfma_f32_32x32x16_bf16 v[66:81], v[158:161], v[154:157], v[66:81]
	v_readfirstlane_b32 s8, v183
	s_mov_b32 m0, s8
	s_nop 0
	global_load_lds_dwordx4 v[176:177], off
	s_waitcnt lgkmcnt(1)
	v_mfma_f32_32x32x16_bf16 v[50:65], v[162:165], v[150:153], v[50:65]
	v_mfma_f32_32x32x16_bf16 v[34:49], v[162:165], v[154:157], v[34:49]
	v_add_u32_e32 v0, 0x4400, v182
	v_lshl_add_u64 v[146:147], v[174:175], 0, s[90:91]
	v_readfirstlane_b32 s8, v0
	s_mov_b32 m0, s8
	s_nop 0
	global_load_lds_dwordx4 v[146:147], off
	s_waitcnt lgkmcnt(0)
	v_mfma_f32_32x32x16_bf16 v[18:33], v[166:169], v[150:153], v[18:33]
	v_mfma_f32_32x32x16_bf16 v[2:17], v[166:169], v[154:157], v[2:17]
	s_setprio 0
	s_add_i32 s8, s7, 1
	s_cmp_lt_i32 s7, 2
	s_cselect_b32 s7, s8, 0
	s_add_u32 s2, s2, 0x80
	s_addc_u32 s3, s3, 0
	s_cmpk_eq_i32 s2, 0xf00
	s_cbranch_scc0 .LBB0_220
	s_waitcnt vmcnt(6)
	s_mul_i32 s2, s7, 0x6000
	s_waitcnt lgkmcnt(0)
	v_add_u32_e32 v139, s2, v224
	v_add_u32_e32 v0, s2, v223
	v_add_u32_e32 v150, v139, v228
	s_barrier
	v_add_u32_e32 v141, v0, v228
	ds_read_b128 v[142:145], v141
	ds_read_b128 v[146:149], v150
	ds_read_b128 v[150:153], v150 offset:2048
	ds_read_b128 v[154:157], v141 offset:2048
	ds_read_b128 v[158:161], v141 offset:4096
	ds_read_b128 v[162:165], v141 offset:6144
	s_waitcnt lgkmcnt(3)
	s_setprio 1
	v_mfma_f32_32x32x16_bf16 v[114:129], v[142:145], v[146:149], v[114:129]
	v_mfma_f32_32x32x16_bf16 v[98:113], v[142:145], v[150:153], v[98:113]
	s_waitcnt lgkmcnt(2)
	v_mfma_f32_32x32x16_bf16 v[82:97], v[154:157], v[146:149], v[82:97]
	v_mfma_f32_32x32x16_bf16 v[66:81], v[154:157], v[150:153], v[66:81]
	s_waitcnt lgkmcnt(1)
	v_mfma_f32_32x32x16_bf16 v[50:65], v[158:161], v[146:149], v[50:65]
	v_mfma_f32_32x32x16_bf16 v[34:49], v[158:161], v[150:153], v[34:49]
	s_waitcnt lgkmcnt(0)
	v_mfma_f32_32x32x16_bf16 v[18:33], v[162:165], v[146:149], v[18:33]
	v_mfma_f32_32x32x16_bf16 v[2:17], v[162:165], v[150:153], v[2:17]
	s_setprio 0
	v_add_u32_e32 v0, v0, v229
	v_add_u32_e32 v139, v139, v229
	ds_read_b128 v[142:145], v0
	ds_read_b128 v[146:149], v139
	ds_read_b128 v[150:153], v139 offset:2048
	ds_read_b128 v[154:157], v0 offset:2048
	ds_read_b128 v[158:161], v0 offset:4096
	ds_read_b128 v[162:165], v0 offset:6144
	s_waitcnt lgkmcnt(3)
	s_setprio 1
	v_mfma_f32_32x32x16_bf16 v[114:129], v[142:145], v[146:149], v[114:129]
	v_mfma_f32_32x32x16_bf16 v[98:113], v[142:145], v[150:153], v[98:113]
	s_waitcnt lgkmcnt(2)
	v_mfma_f32_32x32x16_bf16 v[82:97], v[154:157], v[146:149], v[82:97]
	v_mfma_f32_32x32x16_bf16 v[66:81], v[154:157], v[150:153], v[66:81]
	s_waitcnt lgkmcnt(1)
	v_mfma_f32_32x32x16_bf16 v[50:65], v[158:161], v[146:149], v[50:65]
	v_mfma_f32_32x32x16_bf16 v[34:49], v[158:161], v[150:153], v[34:49]
	s_waitcnt lgkmcnt(0)
	v_mfma_f32_32x32x16_bf16 v[18:33], v[162:165], v[146:149], v[18:33]
	v_mfma_f32_32x32x16_bf16 v[2:17], v[162:165], v[150:153], v[2:17]
	s_setprio 0
	s_waitcnt vmcnt(0)
	s_waitcnt lgkmcnt(0)
	s_barrier
	ds_read_b128 v[142:145], v232
	ds_read_b128 v[146:149], v233
	ds_read_b128 v[150:153], v233 offset:2048
	ds_read_b128 v[154:157], v232 offset:2048
	ds_read_b128 v[158:161], v232 offset:4096
	ds_read_b128 v[162:165], v232 offset:6144
	s_waitcnt lgkmcnt(3)
	s_setprio 1
	v_mfma_f32_32x32x16_bf16 v[114:129], v[142:145], v[146:149], v[114:129]
	v_mfma_f32_32x32x16_bf16 v[98:113], v[142:145], v[150:153], v[98:113]
	s_waitcnt lgkmcnt(2)
	v_mfma_f32_32x32x16_bf16 v[82:97], v[154:157], v[146:149], v[82:97]
	v_mfma_f32_32x32x16_bf16 v[66:81], v[154:157], v[150:153], v[66:81]
	s_waitcnt lgkmcnt(1)
	v_mfma_f32_32x32x16_bf16 v[50:65], v[158:161], v[146:149], v[50:65]
	v_mfma_f32_32x32x16_bf16 v[34:49], v[158:161], v[150:153], v[34:49]
	s_waitcnt lgkmcnt(0)
	v_mfma_f32_32x32x16_bf16 v[18:33], v[162:165], v[146:149], v[18:33]
	v_mfma_f32_32x32x16_bf16 v[2:17], v[162:165], v[150:153], v[2:17]
	s_setprio 0
	ds_read_b128 v[142:145], v234
	ds_read_b128 v[146:149], v235
	ds_read_b128 v[150:153], v235 offset:2048
	ds_read_b128 v[154:157], v234 offset:2048
	ds_read_b128 v[158:161], v234 offset:4096
	ds_read_b128 v[162:165], v234 offset:6144
	s_waitcnt lgkmcnt(3)
	s_setprio 1
	v_mfma_f32_32x32x16_bf16 v[114:129], v[142:145], v[146:149], v[114:129]
	v_mfma_f32_32x32x16_bf16 v[98:113], v[142:145], v[150:153], v[98:113]
	s_waitcnt lgkmcnt(2)
	v_mfma_f32_32x32x16_bf16 v[82:97], v[154:157], v[146:149], v[82:97]
	v_mfma_f32_32x32x16_bf16 v[66:81], v[154:157], v[150:153], v[66:81]
	s_waitcnt lgkmcnt(1)
	v_mfma_f32_32x32x16_bf16 v[50:65], v[158:161], v[146:149], v[50:65]
	v_mfma_f32_32x32x16_bf16 v[34:49], v[158:161], v[150:153], v[34:49]
	s_waitcnt lgkmcnt(0)
	v_mfma_f32_32x32x16_bf16 v[18:33], v[162:165], v[146:149], v[18:33]
	v_mfma_f32_32x32x16_bf16 v[2:17], v[162:165], v[150:153], v[2:17]
	s_setprio 0
	s_cmp_gt_i32 s4, 3
	s_cselect_b64 s[30:31], -1, 0
	s_add_i32 s2, s4, -8
	s_cmp_gt_u32 s2, 5
	s_cselect_b64 s[98:99], -1, 0
	s_and_b32 s2, s4, 0x7ffffffc
	s_cmp_lg_u32 s2, 20
	v_add_u32_e32 v238, s5, v225
	s_cselect_b64 s[2:3], -1, 0
	s_and_b32 s5, s4, 0x7ffffffe
	s_cmp_eq_u32 s5, 6
	s_cselect_b64 s[82:83], -1, 0
	s_sub_i32 s5, s4, 17
	v_add_u32_e32 v239, 0x800, v230
	v_add_u32_e32 v240, 0x1000, v230
	v_add_u32_e32 v241, 0x1800, v230
	s_waitcnt vmcnt(0) lgkmcnt(0)
	s_barrier
	s_cmp_lt_u32 s5, 3
	ds_write2_b32 v230, v114, v98 offset1:32
	ds_write2_b32 v230, v115, v99 offset0:65 offset1:97
	ds_write2_b32 v230, v116, v100 offset0:130 offset1:162
	ds_write2_b32 v230, v117, v101 offset0:195 offset1:227
	ds_write2_b32 v239, v118, v102 offset0:8 offset1:40
	ds_write2_b32 v239, v119, v103 offset0:73 offset1:105
	ds_write2_b32 v239, v120, v104 offset0:138 offset1:170
	ds_write2_b32 v239, v121, v105 offset0:203 offset1:235
	ds_write2_b32 v240, v122, v106 offset0:16 offset1:48
	ds_write2_b32 v240, v123, v107 offset0:81 offset1:113
	ds_write2_b32 v240, v124, v108 offset0:146 offset1:178
	ds_write2_b32 v240, v125, v109 offset0:211 offset1:243
	ds_write2_b32 v241, v126, v110 offset0:24 offset1:56
	ds_write2_b32 v241, v127, v111 offset0:89 offset1:121
	ds_write2_b32 v241, v128, v112 offset0:154 offset1:186
	ds_write2_b32 v241, v129, v113 offset0:219 offset1:251
	s_cselect_b64 s[8:9], -1, 0
	s_cmp_gt_u32 s4, 26
	s_waitcnt lgkmcnt(0)
	s_cselect_b64 s[34:35], -1, 0
	ds_read2_b32 v[154:155], v231 offset0:16 offset1:17
	ds_read2_b32 v[128:129], v231 offset0:18 offset1:19
	ds_read2_b32 v[126:127], v231 offset0:20 offset1:21
	ds_read2_b32 v[124:125], v231 offset0:22 offset1:23
	ds_read2_b32 v[122:123], v231 offset1:1
	ds_read2_b32 v[120:121], v231 offset0:4 offset1:5
	ds_read2_b32 v[114:115], v231 offset0:6 offset1:7
	ds_read2_b32 v[116:117], v231 offset0:2 offset1:3
	ds_read2_b32 v[162:163], v231 offset0:8 offset1:9
	ds_read2_b32 v[160:161], v231 offset0:10 offset1:11
	ds_read2_b32 v[158:159], v231 offset0:12 offset1:13
	ds_read2_b32 v[156:157], v231 offset0:14 offset1:15
	ds_read2_b32 v[152:153], v231 offset0:24 offset1:25
	ds_read2_b32 v[150:151], v231 offset0:26 offset1:27
	ds_read2_b32 v[148:149], v231 offset0:28 offset1:29
	ds_read2_b32 v[146:147], v231 offset0:30 offset1:31
	s_or_b64 s[8:9], s[34:35], s[8:9]
	s_cmp_gt_u32 s4, 21
	s_cselect_b64 vcc, -1, 0
	s_cmp_lt_u32 s4, 11
	v_cndmask_b32_e32 v144, 1.0, v213, vcc
	s_cselect_b64 vcc, -1, 0
	s_and_b64 s[34:35], vcc, exec
	s_cselect_b32 s7, s84, s86
	v_readlane_b32 s34, v242, 4
	s_cselect_b32 s5, s85, s87
	v_readlane_b32 s35, v242, 5
	s_add_u32 s34, s7, s34
	s_addc_u32 s35, s5, s35
	s_cmp_lt_i32 s4, 2
	v_mov_b32_e32 v141, v1
	s_cselect_b64 s[4:5], -1, 0
	v_lshl_add_u64 v[142:143], s[34:35], 0, v[140:141]
	s_and_b64 s[34:35], s[4:5], exec
	s_cselect_b32 s34, s28, s94
	v_readlane_b32 s36, v242, 12
	s_cselect_b32 s7, s29, s95
	v_readlane_b32 s37, v242, 13
	s_add_u32 s34, s34, s36
	s_addc_u32 s35, s7, s37
	s_movk_i32 s7, 0xf80
	v_and_or_b32 v0, v238, s7, v131
	s_waitcnt lgkmcnt(0)
	v_mul_u32_u24_e32 v0, 0x48, v0
	v_lshlrev_b32_e32 v0, 2, v0
	v_cndmask_b32_e32 v139, 1.0, v214, vcc
	v_lshl_add_u64 v[118:119], s[92:93], 0, v[0:1]
	s_mov_b64 s[96:97], -1
	s_and_b64 vcc, exec, s[30:31]
	s_cbranch_vccz .LBB0_239
	s_and_b64 vcc, exec, s[98:99]
	s_cbranch_vccz .LBB0_234
	s_and_b64 vcc, exec, s[2:3]
	s_cbranch_vccz .LBB0_227
	s_or_b64 s[68:69], s[82:83], s[8:9]
	s_andn2_b64 vcc, exec, s[68:69]
	s_waitcnt lgkmcnt(3)
	v_mov_b64_e32 v[110:111], v[152:153]
	s_waitcnt lgkmcnt(2)
	v_mov_b64_e32 v[112:113], v[150:151]
	s_waitcnt lgkmcnt(1)
	v_mov_b64_e32 v[172:173], v[148:149]
	s_waitcnt lgkmcnt(0)
	v_mov_b64_e32 v[174:175], v[146:147]
	v_mov_b64_e32 v[176:177], v[154:155]
	v_mov_b64_e32 v[178:179], v[128:129]
	v_mov_b64_e32 v[180:181], v[126:127]
	v_mov_b64_e32 v[190:191], v[124:125]
	v_mov_b64_e32 v[164:165], v[162:163]
	v_mov_b64_e32 v[166:167], v[160:161]
	v_mov_b64_e32 v[168:169], v[158:159]
	v_mov_b64_e32 v[170:171], v[156:157]
	v_mov_b64_e32 v[182:183], v[122:123]
	v_mov_b64_e32 v[188:189], v[116:117]
	v_mov_b64_e32 v[186:187], v[120:121]
	v_mov_b64_e32 v[184:185], v[114:115]
	s_cbranch_vccnz .LBB0_226
	v_mul_f32_e32 v0, 0xbfb8aa3b, v122
	v_exp_f32_e32 v0, v0
	v_mul_f32_e32 v98, 0xbfb8aa3b, v123
	v_exp_f32_e32 v98, v98
	v_mul_f32_e32 v100, 0xbfb8aa3b, v117
	v_add_f32_e32 v0, 1.0, v0
	v_exp_f32_e32 v100, v100
	v_add_f32_e32 v99, 1.0, v98
	v_rcp_f32_e32 v98, v0
	v_mul_f32_e32 v0, 0xbfb8aa3b, v116
	v_exp_f32_e32 v0, v0
	v_rcp_f32_e32 v99, v99
	v_add_f32_e32 v0, 1.0, v0
	v_pk_mul_f32 v[182:183], v[122:123], v[98:99]
	v_rcp_f32_e32 v98, v0
	v_add_f32_e32 v0, 1.0, v100
	v_rcp_f32_e32 v99, v0
	v_mul_f32_e32 v0, 0xbfb8aa3b, v120
	v_exp_f32_e32 v0, v0
	v_mul_f32_e32 v100, 0xbfb8aa3b, v121
	v_exp_f32_e32 v100, v100
	v_pk_mul_f32 v[188:189], v[116:117], v[98:99]
	v_add_f32_e32 v0, 1.0, v0
	v_rcp_f32_e32 v98, v0
	v_add_f32_e32 v0, 1.0, v100
	v_rcp_f32_e32 v99, v0
	v_mul_f32_e32 v0, 0xbfb8aa3b, v114
	v_exp_f32_e32 v0, v0
	v_mul_f32_e32 v100, 0xbfb8aa3b, v115
	v_exp_f32_e32 v100, v100
	v_pk_mul_f32 v[186:187], v[120:121], v[98:99]
	v_add_f32_e32 v0, 1.0, v0
	v_rcp_f32_e32 v98, v0
	v_add_f32_e32 v0, 1.0, v100
	v_rcp_f32_e32 v99, v0
	v_mul_f32_e32 v0, 0xbfb8aa3b, v162
	v_exp_f32_e32 v0, v0
	v_mul_f32_e32 v100, 0xbfb8aa3b, v163
	v_exp_f32_e32 v100, v100
	v_pk_mul_f32 v[184:185], v[114:115], v[98:99]
	v_add_f32_e32 v0, 1.0, v0
	v_rcp_f32_e32 v98, v0
	v_add_f32_e32 v0, 1.0, v100
	v_rcp_f32_e32 v99, v0
	v_mul_f32_e32 v0, 0xbfb8aa3b, v160
	v_exp_f32_e32 v0, v0
	v_mul_f32_e32 v100, 0xbfb8aa3b, v161
	v_exp_f32_e32 v100, v100
	v_pk_mul_f32 v[164:165], v[162:163], v[98:99]
	v_add_f32_e32 v0, 1.0, v0
	v_rcp_f32_e32 v98, v0
	v_add_f32_e32 v0, 1.0, v100
	v_rcp_f32_e32 v99, v0
	v_mul_f32_e32 v0, 0xbfb8aa3b, v158
	v_exp_f32_e32 v0, v0
	v_mul_f32_e32 v100, 0xbfb8aa3b, v159
	v_exp_f32_e32 v100, v100
	v_pk_mul_f32 v[166:167], v[160:161], v[98:99]
	v_add_f32_e32 v0, 1.0, v0
	v_rcp_f32_e32 v98, v0
	v_add_f32_e32 v0, 1.0, v100
	v_rcp_f32_e32 v99, v0
	v_mul_f32_e32 v0, 0xbfb8aa3b, v156
	v_exp_f32_e32 v0, v0
	v_mul_f32_e32 v100, 0xbfb8aa3b, v157
	v_exp_f32_e32 v100, v100
	v_pk_mul_f32 v[168:169], v[158:159], v[98:99]
	v_add_f32_e32 v0, 1.0, v0
	v_rcp_f32_e32 v98, v0
	v_add_f32_e32 v0, 1.0, v100
	v_rcp_f32_e32 v99, v0
	v_mul_f32_e32 v0, 0xbfb8aa3b, v154
	v_exp_f32_e32 v0, v0
	v_mul_f32_e32 v100, 0xbfb8aa3b, v155
	v_exp_f32_e32 v100, v100
	v_pk_mul_f32 v[170:171], v[156:157], v[98:99]
	v_add_f32_e32 v0, 1.0, v0
	v_rcp_f32_e32 v98, v0
	v_add_f32_e32 v0, 1.0, v100
	v_rcp_f32_e32 v99, v0
	v_mul_f32_e32 v0, 0xbfb8aa3b, v128
	v_exp_f32_e32 v0, v0
	v_mul_f32_e32 v100, 0xbfb8aa3b, v129
	v_exp_f32_e32 v100, v100
	v_pk_mul_f32 v[176:177], v[154:155], v[98:99]
	v_add_f32_e32 v0, 1.0, v0
	v_rcp_f32_e32 v98, v0
	v_add_f32_e32 v0, 1.0, v100
	v_rcp_f32_e32 v99, v0
	v_mul_f32_e32 v0, 0xbfb8aa3b, v126
	v_exp_f32_e32 v0, v0
	v_mul_f32_e32 v100, 0xbfb8aa3b, v127
	v_exp_f32_e32 v100, v100
	v_pk_mul_f32 v[178:179], v[128:129], v[98:99]
	v_add_f32_e32 v0, 1.0, v0
	v_rcp_f32_e32 v98, v0
	v_add_f32_e32 v0, 1.0, v100
	v_rcp_f32_e32 v99, v0
	v_mul_f32_e32 v0, 0xbfb8aa3b, v124
	v_exp_f32_e32 v0, v0
	v_mul_f32_e32 v100, 0xbfb8aa3b, v125
	v_exp_f32_e32 v100, v100
	v_pk_mul_f32 v[180:181], v[126:127], v[98:99]
	v_add_f32_e32 v0, 1.0, v0
	v_rcp_f32_e32 v98, v0
	v_add_f32_e32 v0, 1.0, v100
	v_rcp_f32_e32 v99, v0
	v_mul_f32_e32 v0, 0xbfb8aa3b, v152
	v_exp_f32_e32 v0, v0
	v_mul_f32_e32 v100, 0xbfb8aa3b, v153
	v_exp_f32_e32 v100, v100
	v_pk_mul_f32 v[190:191], v[124:125], v[98:99]
	v_add_f32_e32 v0, 1.0, v0
	v_mul_f32_e32 v99, 0xbfb8aa3b, v150
	v_rcp_f32_e32 v98, v0
	v_add_f32_e32 v0, 1.0, v100
	v_exp_f32_e32 v100, v99
	v_mul_f32_e32 v99, 0xbfb8aa3b, v151
	v_exp_f32_e32 v101, v99
	v_rcp_f32_e32 v99, v0
	v_add_f32_e32 v0, 1.0, v100
	v_rcp_f32_e32 v100, v0
	v_add_f32_e32 v0, 1.0, v101
	v_mul_f32_e32 v101, 0xbfb8aa3b, v148
	v_exp_f32_e32 v102, v101
	v_mul_f32_e32 v101, 0xbfb8aa3b, v149
	v_exp_f32_e32 v103, v101
	v_rcp_f32_e32 v101, v0
	v_add_f32_e32 v0, 1.0, v102
	v_rcp_f32_e32 v102, v0
	v_add_f32_e32 v0, 1.0, v103
	v_mul_f32_e32 v103, 0xbfb8aa3b, v146
	v_exp_f32_e32 v104, v103
	v_mul_f32_e32 v103, 0xbfb8aa3b, v147
	v_exp_f32_e32 v105, v103
	v_rcp_f32_e32 v103, v0
	v_add_f32_e32 v0, 1.0, v104
	v_rcp_f32_e32 v104, v0
	v_add_f32_e32 v0, 1.0, v105
	v_rcp_f32_e32 v105, v0
	v_pk_mul_f32 v[110:111], v[152:153], v[98:99]
	v_pk_mul_f32 v[112:113], v[150:151], v[100:101]
	v_pk_mul_f32 v[172:173], v[148:149], v[102:103]
	v_pk_mul_f32 v[174:175], v[146:147], v[104:105]
